# norm1/norm2 phases hand-written: three rows of x in flight per wave, gamma loaded once, adaLN shift/scale once per condition, DPP row reduction (compiled loop exposed every load round trip, 6 rows x 4
# speedup vs baseline: 1.0772x; 1.0113x over previous
.LBB0_364:
	s_cmp_lg_u32 s84, 0x100
	s_cbranch_scc1 .Lnm2_orig
	v_readlane_b32 s4, v251, 0
	v_readfirstlane_b32 s5, v135
	v_readlane_b32 s6, v249, 47
	s_lshr_b32 s5, s5, 6
	s_lshl_b32 s4, s4, 3
	s_add_i32 s4, s4, s5
	v_readlane_b32 s8, v251, 25
	v_readlane_b32 s9, v251, 26
	v_readlane_b32 s10, v251, 23
	v_readlane_b32 s11, v251, 24
	v_readlane_b32 s12, v249, 37
	v_readlane_b32 s13, v249, 38
	v_mbcnt_lo_u32_b32 v0, -1, 0
	v_mbcnt_hi_u32_b32 v0, -1, v0
	v_lshlrev_b32_e32 v12, 4, v0
	v_lshlrev_b32_e32 v13, 3, v0
	v_xor_b32_e32 v6, 32, v0
	v_lshlrev_b32_e32 v6, 2, v6
	v_xor_b32_e32 v7, 16, v0
	v_lshlrev_b32_e32 v7, 2, v7
	v_xor_b32_e32 v8, 8, v0
	v_lshlrev_b32_e32 v8, 2, v8
	v_xor_b32_e32 v9, 4, v0
	v_lshlrev_b32_e32 v9, 2, v9
	v_xor_b32_e32 v10, 2, v0
	v_lshlrev_b32_e32 v10, 2, v10
	v_xor_b32_e32 v11, 1, v0
	v_lshlrev_b32_e32 v11, 2, v11
	v_mov_b32_e32 v18, 0x358637bd
	s_lshl_b32 s14, s6, 12
	s_add_u32 s12, s12, s14
	s_addc_u32 s13, s13, 0
	s_mul_i32 s15, s6, 3
	s_mul_i32 s15, s15, 0x6000
	s_add_u32 s16, s94, 0x12d43000
	s_addc_u32 s17, s95, 0
	s_add_u32 s16, s16, s15
	s_addc_u32 s17, s17, 0
	s_lshl_b32 s14, s4, 12
	s_mov_b32 s54, s14
	s_add_u32 s18, s8, s14
	s_addc_u32 s19, s9, 0
	s_lshl_b32 s14, s4, 11
	s_add_u32 s44, s10, s14
	s_addc_u32 s45, s11, 0
	global_load_dwordx4 v[30:33], v12, s[18:19]
	global_load_dwordx4 v[34:37], v12, s[18:19] offset:1024
	global_load_dwordx4 v[38:41], v12, s[18:19] offset:2048
	global_load_dwordx4 v[42:45], v12, s[18:19] offset:3072
	s_add_u32 s18, s18, 0x800000
	s_addc_u32 s19, s19, 0
	global_load_dwordx4 v[46:49], v12, s[18:19]
	global_load_dwordx4 v[50:53], v12, s[18:19] offset:1024
	global_load_dwordx4 v[54:57], v12, s[18:19] offset:2048
	global_load_dwordx4 v[58:61], v12, s[18:19] offset:3072
	s_add_u32 s18, s18, 0x800000
	s_addc_u32 s19, s19, 0
	global_load_dwordx4 v[62:65], v12, s[18:19]
	global_load_dwordx4 v[66:69], v12, s[18:19] offset:1024
	global_load_dwordx4 v[70:73], v12, s[18:19] offset:2048
	global_load_dwordx4 v[74:77], v12, s[18:19] offset:3072
	s_add_u32 s18, s18, 0x800000
	s_addc_u32 s19, s19, 0
	global_load_dwordx4 v[78:81], v12, s[12:13]
	global_load_dwordx4 v[82:85], v12, s[12:13] offset:1024
	global_load_dwordx4 v[86:89], v12, s[12:13] offset:2048
	global_load_dwordx4 v[90:93], v12, s[12:13] offset:3072
	s_add_u32 s48, s16, 0x0
	s_addc_u32 s49, s17, 0
	s_add_u32 s50, s48, 0x1000
	s_addc_u32 s51, s49, 0
	global_load_dwordx4 v[94:97], v12, s[50:51]
	global_load_dwordx4 v[98:101], v12, s[50:51] offset:1024
	global_load_dwordx4 v[102:105], v12, s[50:51] offset:2048
	global_load_dwordx4 v[106:109], v12, s[50:51] offset:3072
	global_load_dwordx4 v[110:113], v12, s[48:49]
	global_load_dwordx4 v[114:117], v12, s[48:49] offset:1024
	global_load_dwordx4 v[118:121], v12, s[48:49] offset:2048
	global_load_dwordx4 v[122:125], v12, s[48:49] offset:3072
	s_add_u32 s48, s16, 0x6000
	s_addc_u32 s49, s17, 0
	s_add_u32 s50, s48, 0x1000
	s_addc_u32 s51, s49, 0
	global_load_dwordx4 v[126:129], v12, s[50:51]
	global_load_dwordx4 v[130:133], v12, s[50:51] offset:1024
	global_load_dwordx4 v[138:141], v12, s[50:51] offset:2048
	global_load_dwordx4 v[142:145], v12, s[50:51] offset:3072
	global_load_dwordx4 v[146:149], v12, s[48:49]
	global_load_dwordx4 v[150:153], v12, s[48:49] offset:1024
	global_load_dwordx4 v[154:157], v12, s[48:49] offset:2048
	global_load_dwordx4 v[158:161], v12, s[48:49] offset:3072
	s_waitcnt vmcnt(28)
	v_pk_mul_f32 v[24:25], v[30:31], v[30:31]
	v_pk_mul_f32 v[26:27], v[32:33], v[32:33]
	v_pk_fma_f32 v[24:25], v[34:35], v[34:35], v[24:25]
	v_pk_fma_f32 v[26:27], v[36:37], v[36:37], v[26:27]
	v_pk_fma_f32 v[24:25], v[38:39], v[38:39], v[24:25]
	v_pk_fma_f32 v[26:27], v[40:41], v[40:41], v[26:27]
	v_pk_fma_f32 v[24:25], v[42:43], v[42:43], v[24:25]
	v_pk_fma_f32 v[26:27], v[44:45], v[44:45], v[26:27]
	v_pk_add_f32 v[24:25], v[24:25], v[26:27]
	s_nop 0
	v_add_f32_e32 v19, v24, v25
	s_nop 1
	v_add_f32_dpp v19, v19, v19 quad_perm:[1,0,3,2] row_mask:0xf bank_mask:0xf
	s_nop 1
	v_add_f32_dpp v19, v19, v19 quad_perm:[2,3,0,1] row_mask:0xf bank_mask:0xf
	s_nop 1
	v_add_f32_dpp v19, v19, v19 row_half_mirror row_mask:0xf bank_mask:0xf
	s_nop 1
	v_add_f32_dpp v19, v19, v19 row_mirror row_mask:0xf bank_mask:0xf
	ds_bpermute_b32 v20, v7, v19
	s_waitcnt lgkmcnt(0)
	v_add_f32_e32 v19, v19, v20
	ds_bpermute_b32 v20, v6, v19
	s_waitcnt lgkmcnt(0)
	v_add_f32_e32 v19, v19, v20
	v_fmamk_f32 v19, v19, 0x3a800000, v18
	v_rsq_f32_e32 v22, v19
	s_waitcnt vmcnt(16)
	s_waitcnt vmcnt(8)
	v_pk_add_f32 v[94:95], v[94:95], 1.0 op_sel_hi:[1,0]
	v_pk_add_f32 v[96:97], v[96:97], 1.0 op_sel_hi:[1,0]
	v_pk_add_f32 v[98:99], v[98:99], 1.0 op_sel_hi:[1,0]
	v_pk_add_f32 v[100:101], v[100:101], 1.0 op_sel_hi:[1,0]
	v_pk_add_f32 v[102:103], v[102:103], 1.0 op_sel_hi:[1,0]
	v_pk_add_f32 v[104:105], v[104:105], 1.0 op_sel_hi:[1,0]
	v_pk_add_f32 v[106:107], v[106:107], 1.0 op_sel_hi:[1,0]
	v_pk_add_f32 v[108:109], v[108:109], 1.0 op_sel_hi:[1,0]
	s_nop 0
	v_pk_mul_f32 v[30:31], v[30:31], v[22:23] op_sel_hi:[1,0]
	v_pk_mul_f32 v[32:33], v[32:33], v[22:23] op_sel_hi:[1,0]
	v_pk_mul_f32 v[30:31], v[78:79], v[30:31]
	v_pk_mul_f32 v[32:33], v[80:81], v[32:33]
	v_pk_fma_f32 v[30:31], v[94:95], v[30:31], v[110:111]
	v_pk_fma_f32 v[32:33], v[96:97], v[32:33], v[112:113]
	v_cvt_pk_bf16_f32 v30, v30, v31
	v_cvt_pk_bf16_f32 v31, v32, v33
	global_store_dwordx2 v13, v[30:31], s[44:45]
	v_pk_mul_f32 v[34:35], v[34:35], v[22:23] op_sel_hi:[1,0]
	v_pk_mul_f32 v[36:37], v[36:37], v[22:23] op_sel_hi:[1,0]
	v_pk_mul_f32 v[34:35], v[82:83], v[34:35]
	v_pk_mul_f32 v[36:37], v[84:85], v[36:37]
	v_pk_fma_f32 v[34:35], v[98:99], v[34:35], v[114:115]
	v_pk_fma_f32 v[36:37], v[100:101], v[36:37], v[116:117]
	v_cvt_pk_bf16_f32 v34, v34, v35
	v_cvt_pk_bf16_f32 v35, v36, v37
	global_store_dwordx2 v13, v[34:35], s[44:45] offset:512
	v_pk_mul_f32 v[38:39], v[38:39], v[22:23] op_sel_hi:[1,0]
	v_pk_mul_f32 v[40:41], v[40:41], v[22:23] op_sel_hi:[1,0]
	v_pk_mul_f32 v[38:39], v[86:87], v[38:39]
	v_pk_mul_f32 v[40:41], v[88:89], v[40:41]
	v_pk_fma_f32 v[38:39], v[102:103], v[38:39], v[118:119]
	v_pk_fma_f32 v[40:41], v[104:105], v[40:41], v[120:121]
	v_cvt_pk_bf16_f32 v38, v38, v39
	v_cvt_pk_bf16_f32 v39, v40, v41
	global_store_dwordx2 v13, v[38:39], s[44:45] offset:1024
	v_pk_mul_f32 v[42:43], v[42:43], v[22:23] op_sel_hi:[1,0]
	v_pk_mul_f32 v[44:45], v[44:45], v[22:23] op_sel_hi:[1,0]
	v_pk_mul_f32 v[42:43], v[90:91], v[42:43]
	v_pk_mul_f32 v[44:45], v[92:93], v[44:45]
	v_pk_fma_f32 v[42:43], v[106:107], v[42:43], v[122:123]
	v_pk_fma_f32 v[44:45], v[108:109], v[44:45], v[124:125]
	v_cvt_pk_bf16_f32 v42, v42, v43
	v_cvt_pk_bf16_f32 v43, v44, v45
	global_store_dwordx2 v13, v[42:43], s[44:45] offset:1536
	s_add_u32 s44, s44, 0x400000
	s_addc_u32 s45, s45, 0
	global_load_dwordx4 v[30:33], v12, s[18:19]
	global_load_dwordx4 v[34:37], v12, s[18:19] offset:1024
	global_load_dwordx4 v[38:41], v12, s[18:19] offset:2048
	global_load_dwordx4 v[42:45], v12, s[18:19] offset:3072
	s_add_u32 s18, s18, 0x800000
	s_addc_u32 s19, s19, 0
	s_waitcnt vmcnt(32)
	v_pk_mul_f32 v[24:25], v[46:47], v[46:47]
	v_pk_mul_f32 v[26:27], v[48:49], v[48:49]
	v_pk_fma_f32 v[24:25], v[50:51], v[50:51], v[24:25]
	v_pk_fma_f32 v[26:27], v[52:53], v[52:53], v[26:27]
	v_pk_fma_f32 v[24:25], v[54:55], v[54:55], v[24:25]
	v_pk_fma_f32 v[26:27], v[56:57], v[56:57], v[26:27]
	v_pk_fma_f32 v[24:25], v[58:59], v[58:59], v[24:25]
	v_pk_fma_f32 v[26:27], v[60:61], v[60:61], v[26:27]
	v_pk_add_f32 v[24:25], v[24:25], v[26:27]
	s_nop 0
	v_add_f32_e32 v19, v24, v25
	s_nop 1
	v_add_f32_dpp v19, v19, v19 quad_perm:[1,0,3,2] row_mask:0xf bank_mask:0xf
	s_nop 1
	v_add_f32_dpp v19, v19, v19 quad_perm:[2,3,0,1] row_mask:0xf bank_mask:0xf
	s_nop 1
	v_add_f32_dpp v19, v19, v19 row_half_mirror row_mask:0xf bank_mask:0xf
	s_nop 1
	v_add_f32_dpp v19, v19, v19 row_mirror row_mask:0xf bank_mask:0xf
	ds_bpermute_b32 v20, v7, v19
	s_waitcnt lgkmcnt(0)
	v_add_f32_e32 v19, v19, v20
	ds_bpermute_b32 v20, v6, v19
	s_waitcnt lgkmcnt(0)
	v_add_f32_e32 v19, v19, v20
	v_fmamk_f32 v19, v19, 0x3a800000, v18
	v_rsq_f32_e32 v22, v19
	s_nop 0
	v_pk_mul_f32 v[46:47], v[46:47], v[22:23] op_sel_hi:[1,0]
	v_pk_mul_f32 v[48:49], v[48:49], v[22:23] op_sel_hi:[1,0]
	v_pk_mul_f32 v[46:47], v[78:79], v[46:47]
	v_pk_mul_f32 v[48:49], v[80:81], v[48:49]
	v_pk_fma_f32 v[46:47], v[94:95], v[46:47], v[110:111]
	v_pk_fma_f32 v[48:49], v[96:97], v[48:49], v[112:113]
	v_cvt_pk_bf16_f32 v46, v46, v47
	v_cvt_pk_bf16_f32 v47, v48, v49
	global_store_dwordx2 v13, v[46:47], s[44:45]
	v_pk_mul_f32 v[50:51], v[50:51], v[22:23] op_sel_hi:[1,0]
	v_pk_mul_f32 v[52:53], v[52:53], v[22:23] op_sel_hi:[1,0]
	v_pk_mul_f32 v[50:51], v[82:83], v[50:51]
	v_pk_mul_f32 v[52:53], v[84:85], v[52:53]
	v_pk_fma_f32 v[50:51], v[98:99], v[50:51], v[114:115]
	v_pk_fma_f32 v[52:53], v[100:101], v[52:53], v[116:117]
	v_cvt_pk_bf16_f32 v50, v50, v51
	v_cvt_pk_bf16_f32 v51, v52, v53
	global_store_dwordx2 v13, v[50:51], s[44:45] offset:512
	v_pk_mul_f32 v[54:55], v[54:55], v[22:23] op_sel_hi:[1,0]
	v_pk_mul_f32 v[56:57], v[56:57], v[22:23] op_sel_hi:[1,0]
	v_pk_mul_f32 v[54:55], v[86:87], v[54:55]
	v_pk_mul_f32 v[56:57], v[88:89], v[56:57]
	v_pk_fma_f32 v[54:55], v[102:103], v[54:55], v[118:119]
	v_pk_fma_f32 v[56:57], v[104:105], v[56:57], v[120:121]
	v_cvt_pk_bf16_f32 v54, v54, v55
	v_cvt_pk_bf16_f32 v55, v56, v57
	global_store_dwordx2 v13, v[54:55], s[44:45] offset:1024
	v_pk_mul_f32 v[58:59], v[58:59], v[22:23] op_sel_hi:[1,0]
	v_pk_mul_f32 v[60:61], v[60:61], v[22:23] op_sel_hi:[1,0]
	v_pk_mul_f32 v[58:59], v[90:91], v[58:59]
	v_pk_mul_f32 v[60:61], v[92:93], v[60:61]
	v_pk_fma_f32 v[58:59], v[106:107], v[58:59], v[122:123]
	v_pk_fma_f32 v[60:61], v[108:109], v[60:61], v[124:125]
	v_cvt_pk_bf16_f32 v58, v58, v59
	v_cvt_pk_bf16_f32 v59, v60, v61
	global_store_dwordx2 v13, v[58:59], s[44:45] offset:1536
	s_add_u32 s44, s44, 0x400000
	s_addc_u32 s45, s45, 0
	global_load_dwordx4 v[46:49], v12, s[18:19]
	global_load_dwordx4 v[50:53], v12, s[18:19] offset:1024
	global_load_dwordx4 v[54:57], v12, s[18:19] offset:2048
	global_load_dwordx4 v[58:61], v12, s[18:19] offset:3072
	s_add_u32 s18, s18, 0x800000
	s_addc_u32 s19, s19, 0
	s_add_u32 s48, s16, 0xc000
	s_addc_u32 s49, s17, 0
	s_add_u32 s50, s48, 0x1000
	s_addc_u32 s51, s49, 0
	global_load_dwordx4 v[94:97], v12, s[50:51]
	global_load_dwordx4 v[98:101], v12, s[50:51] offset:1024
	global_load_dwordx4 v[102:105], v12, s[50:51] offset:2048
	global_load_dwordx4 v[106:109], v12, s[50:51] offset:3072
	global_load_dwordx4 v[110:113], v12, s[48:49]
	global_load_dwordx4 v[114:117], v12, s[48:49] offset:1024
	global_load_dwordx4 v[118:121], v12, s[48:49] offset:2048
	global_load_dwordx4 v[122:125], v12, s[48:49] offset:3072
	s_waitcnt vmcnt(44)
	v_pk_mul_f32 v[24:25], v[62:63], v[62:63]
	v_pk_mul_f32 v[26:27], v[64:65], v[64:65]
	v_pk_fma_f32 v[24:25], v[66:67], v[66:67], v[24:25]
	v_pk_fma_f32 v[26:27], v[68:69], v[68:69], v[26:27]
	v_pk_fma_f32 v[24:25], v[70:71], v[70:71], v[24:25]
	v_pk_fma_f32 v[26:27], v[72:73], v[72:73], v[26:27]
	v_pk_fma_f32 v[24:25], v[74:75], v[74:75], v[24:25]
	v_pk_fma_f32 v[26:27], v[76:77], v[76:77], v[26:27]
	v_pk_add_f32 v[24:25], v[24:25], v[26:27]
	s_nop 0
	v_add_f32_e32 v19, v24, v25
	s_nop 1
	v_add_f32_dpp v19, v19, v19 quad_perm:[1,0,3,2] row_mask:0xf bank_mask:0xf
	s_nop 1
	v_add_f32_dpp v19, v19, v19 quad_perm:[2,3,0,1] row_mask:0xf bank_mask:0xf
	s_nop 1
	v_add_f32_dpp v19, v19, v19 row_half_mirror row_mask:0xf bank_mask:0xf
	s_nop 1
	v_add_f32_dpp v19, v19, v19 row_mirror row_mask:0xf bank_mask:0xf
	ds_bpermute_b32 v20, v7, v19
	s_waitcnt lgkmcnt(0)
	v_add_f32_e32 v19, v19, v20
	ds_bpermute_b32 v20, v6, v19
	s_waitcnt lgkmcnt(0)
	v_add_f32_e32 v19, v19, v20
	v_fmamk_f32 v19, v19, 0x3a800000, v18
	v_rsq_f32_e32 v22, v19
	s_waitcnt vmcnt(24)
	v_pk_add_f32 v[126:127], v[126:127], 1.0 op_sel_hi:[1,0]
	v_pk_add_f32 v[128:129], v[128:129], 1.0 op_sel_hi:[1,0]
	v_pk_add_f32 v[130:131], v[130:131], 1.0 op_sel_hi:[1,0]
	v_pk_add_f32 v[132:133], v[132:133], 1.0 op_sel_hi:[1,0]
	v_pk_add_f32 v[138:139], v[138:139], 1.0 op_sel_hi:[1,0]
	v_pk_add_f32 v[140:141], v[140:141], 1.0 op_sel_hi:[1,0]
	v_pk_add_f32 v[142:143], v[142:143], 1.0 op_sel_hi:[1,0]
	v_pk_add_f32 v[144:145], v[144:145], 1.0 op_sel_hi:[1,0]
	s_nop 0
	v_pk_mul_f32 v[62:63], v[62:63], v[22:23] op_sel_hi:[1,0]
	v_pk_mul_f32 v[64:65], v[64:65], v[22:23] op_sel_hi:[1,0]
	v_pk_mul_f32 v[62:63], v[78:79], v[62:63]
	v_pk_mul_f32 v[64:65], v[80:81], v[64:65]
	v_pk_fma_f32 v[62:63], v[126:127], v[62:63], v[146:147]
	v_pk_fma_f32 v[64:65], v[128:129], v[64:65], v[148:149]
	v_cvt_pk_bf16_f32 v62, v62, v63
	v_cvt_pk_bf16_f32 v63, v64, v65
	global_store_dwordx2 v13, v[62:63], s[44:45]
	v_pk_mul_f32 v[66:67], v[66:67], v[22:23] op_sel_hi:[1,0]
	v_pk_mul_f32 v[68:69], v[68:69], v[22:23] op_sel_hi:[1,0]
	v_pk_mul_f32 v[66:67], v[82:83], v[66:67]
	v_pk_mul_f32 v[68:69], v[84:85], v[68:69]
	v_pk_fma_f32 v[66:67], v[130:131], v[66:67], v[150:151]
	v_pk_fma_f32 v[68:69], v[132:133], v[68:69], v[152:153]
	v_cvt_pk_bf16_f32 v66, v66, v67
	v_cvt_pk_bf16_f32 v67, v68, v69
	global_store_dwordx2 v13, v[66:67], s[44:45] offset:512
	v_pk_mul_f32 v[70:71], v[70:71], v[22:23] op_sel_hi:[1,0]
	v_pk_mul_f32 v[72:73], v[72:73], v[22:23] op_sel_hi:[1,0]
	v_pk_mul_f32 v[70:71], v[86:87], v[70:71]
	v_pk_mul_f32 v[72:73], v[88:89], v[72:73]
	v_pk_fma_f32 v[70:71], v[138:139], v[70:71], v[154:155]
	v_pk_fma_f32 v[72:73], v[140:141], v[72:73], v[156:157]
	v_cvt_pk_bf16_f32 v70, v70, v71
	v_cvt_pk_bf16_f32 v71, v72, v73
	global_store_dwordx2 v13, v[70:71], s[44:45] offset:1024
	v_pk_mul_f32 v[74:75], v[74:75], v[22:23] op_sel_hi:[1,0]
	v_pk_mul_f32 v[76:77], v[76:77], v[22:23] op_sel_hi:[1,0]
	v_pk_mul_f32 v[74:75], v[90:91], v[74:75]
	v_pk_mul_f32 v[76:77], v[92:93], v[76:77]
	v_pk_fma_f32 v[74:75], v[142:143], v[74:75], v[158:159]
	v_pk_fma_f32 v[76:77], v[144:145], v[76:77], v[160:161]
	v_cvt_pk_bf16_f32 v74, v74, v75
	v_cvt_pk_bf16_f32 v75, v76, v77
	global_store_dwordx2 v13, v[74:75], s[44:45] offset:1536
	s_add_u32 s44, s44, 0x400000
	s_addc_u32 s45, s45, 0
	global_load_dwordx4 v[62:65], v12, s[18:19]
	global_load_dwordx4 v[66:69], v12, s[18:19] offset:1024
	global_load_dwordx4 v[70:73], v12, s[18:19] offset:2048
	global_load_dwordx4 v[74:77], v12, s[18:19] offset:3072
	s_add_u32 s18, s18, 0x800000
	s_addc_u32 s19, s19, 0
	s_waitcnt vmcnt(24)
	v_pk_mul_f32 v[24:25], v[30:31], v[30:31]
	v_pk_mul_f32 v[26:27], v[32:33], v[32:33]
	v_pk_fma_f32 v[24:25], v[34:35], v[34:35], v[24:25]
	v_pk_fma_f32 v[26:27], v[36:37], v[36:37], v[26:27]
	v_pk_fma_f32 v[24:25], v[38:39], v[38:39], v[24:25]
	v_pk_fma_f32 v[26:27], v[40:41], v[40:41], v[26:27]
	v_pk_fma_f32 v[24:25], v[42:43], v[42:43], v[24:25]
	v_pk_fma_f32 v[26:27], v[44:45], v[44:45], v[26:27]
	v_pk_add_f32 v[24:25], v[24:25], v[26:27]
	s_nop 0
	v_add_f32_e32 v19, v24, v25
	s_nop 1
	v_add_f32_dpp v19, v19, v19 quad_perm:[1,0,3,2] row_mask:0xf bank_mask:0xf
	s_nop 1
	v_add_f32_dpp v19, v19, v19 quad_perm:[2,3,0,1] row_mask:0xf bank_mask:0xf
	s_nop 1
	v_add_f32_dpp v19, v19, v19 row_half_mirror row_mask:0xf bank_mask:0xf
	s_nop 1
	v_add_f32_dpp v19, v19, v19 row_mirror row_mask:0xf bank_mask:0xf
	ds_bpermute_b32 v20, v7, v19
	s_waitcnt lgkmcnt(0)
	v_add_f32_e32 v19, v19, v20
	ds_bpermute_b32 v20, v6, v19
	s_waitcnt lgkmcnt(0)
	v_add_f32_e32 v19, v19, v20
	v_fmamk_f32 v19, v19, 0x3a800000, v18
	v_rsq_f32_e32 v22, v19
	s_nop 0
	v_pk_mul_f32 v[30:31], v[30:31], v[22:23] op_sel_hi:[1,0]
	v_pk_mul_f32 v[32:33], v[32:33], v[22:23] op_sel_hi:[1,0]
	v_pk_mul_f32 v[30:31], v[78:79], v[30:31]
	v_pk_mul_f32 v[32:33], v[80:81], v[32:33]
	v_pk_fma_f32 v[30:31], v[126:127], v[30:31], v[146:147]
	v_pk_fma_f32 v[32:33], v[128:129], v[32:33], v[148:149]
	v_cvt_pk_bf16_f32 v30, v30, v31
	v_cvt_pk_bf16_f32 v31, v32, v33
	global_store_dwordx2 v13, v[30:31], s[44:45]
	v_pk_mul_f32 v[34:35], v[34:35], v[22:23] op_sel_hi:[1,0]
	v_pk_mul_f32 v[36:37], v[36:37], v[22:23] op_sel_hi:[1,0]
	v_pk_mul_f32 v[34:35], v[82:83], v[34:35]
	v_pk_mul_f32 v[36:37], v[84:85], v[36:37]
	v_pk_fma_f32 v[34:35], v[130:131], v[34:35], v[150:151]
	v_pk_fma_f32 v[36:37], v[132:133], v[36:37], v[152:153]
	v_cvt_pk_bf16_f32 v34, v34, v35
	v_cvt_pk_bf16_f32 v35, v36, v37
	global_store_dwordx2 v13, v[34:35], s[44:45] offset:512
	v_pk_mul_f32 v[38:39], v[38:39], v[22:23] op_sel_hi:[1,0]
	v_pk_mul_f32 v[40:41], v[40:41], v[22:23] op_sel_hi:[1,0]
	v_pk_mul_f32 v[38:39], v[86:87], v[38:39]
	v_pk_mul_f32 v[40:41], v[88:89], v[40:41]
	v_pk_fma_f32 v[38:39], v[138:139], v[38:39], v[154:155]
	v_pk_fma_f32 v[40:41], v[140:141], v[40:41], v[156:157]
	v_cvt_pk_bf16_f32 v38, v38, v39
	v_cvt_pk_bf16_f32 v39, v40, v41
	global_store_dwordx2 v13, v[38:39], s[44:45] offset:1024
	v_pk_mul_f32 v[42:43], v[42:43], v[22:23] op_sel_hi:[1,0]
	v_pk_mul_f32 v[44:45], v[44:45], v[22:23] op_sel_hi:[1,0]
	v_pk_mul_f32 v[42:43], v[90:91], v[42:43]
	v_pk_mul_f32 v[44:45], v[92:93], v[44:45]
	v_pk_fma_f32 v[42:43], v[142:143], v[42:43], v[158:159]
	v_pk_fma_f32 v[44:45], v[144:145], v[44:45], v[160:161]
	v_cvt_pk_bf16_f32 v42, v42, v43
	v_cvt_pk_bf16_f32 v43, v44, v45
	global_store_dwordx2 v13, v[42:43], s[44:45] offset:1536
	s_add_u32 s44, s44, 0x400000
	s_addc_u32 s45, s45, 0
	s_waitcnt vmcnt(20)
	v_pk_mul_f32 v[24:25], v[46:47], v[46:47]
	v_pk_mul_f32 v[26:27], v[48:49], v[48:49]
	v_pk_fma_f32 v[24:25], v[50:51], v[50:51], v[24:25]
	v_pk_fma_f32 v[26:27], v[52:53], v[52:53], v[26:27]
	v_pk_fma_f32 v[24:25], v[54:55], v[54:55], v[24:25]
	v_pk_fma_f32 v[26:27], v[56:57], v[56:57], v[26:27]
	v_pk_fma_f32 v[24:25], v[58:59], v[58:59], v[24:25]
	v_pk_fma_f32 v[26:27], v[60:61], v[60:61], v[26:27]
	v_pk_add_f32 v[24:25], v[24:25], v[26:27]
	s_nop 0
	v_add_f32_e32 v19, v24, v25
	s_nop 1
	v_add_f32_dpp v19, v19, v19 quad_perm:[1,0,3,2] row_mask:0xf bank_mask:0xf
	s_nop 1
	v_add_f32_dpp v19, v19, v19 quad_perm:[2,3,0,1] row_mask:0xf bank_mask:0xf
	s_nop 1
	v_add_f32_dpp v19, v19, v19 row_half_mirror row_mask:0xf bank_mask:0xf
	s_nop 1
	v_add_f32_dpp v19, v19, v19 row_mirror row_mask:0xf bank_mask:0xf
	ds_bpermute_b32 v20, v7, v19
	s_waitcnt lgkmcnt(0)
	v_add_f32_e32 v19, v19, v20
	ds_bpermute_b32 v20, v6, v19
	s_waitcnt lgkmcnt(0)
	v_add_f32_e32 v19, v19, v20
	v_fmamk_f32 v19, v19, 0x3a800000, v18
	v_rsq_f32_e32 v22, v19
	s_waitcnt vmcnt(12)
	v_pk_add_f32 v[94:95], v[94:95], 1.0 op_sel_hi:[1,0]
	v_pk_add_f32 v[96:97], v[96:97], 1.0 op_sel_hi:[1,0]
	v_pk_add_f32 v[98:99], v[98:99], 1.0 op_sel_hi:[1,0]
	v_pk_add_f32 v[100:101], v[100:101], 1.0 op_sel_hi:[1,0]
	v_pk_add_f32 v[102:103], v[102:103], 1.0 op_sel_hi:[1,0]
	v_pk_add_f32 v[104:105], v[104:105], 1.0 op_sel_hi:[1,0]
	v_pk_add_f32 v[106:107], v[106:107], 1.0 op_sel_hi:[1,0]
	v_pk_add_f32 v[108:109], v[108:109], 1.0 op_sel_hi:[1,0]
	s_nop 0
	v_pk_mul_f32 v[46:47], v[46:47], v[22:23] op_sel_hi:[1,0]
	v_pk_mul_f32 v[48:49], v[48:49], v[22:23] op_sel_hi:[1,0]
	v_pk_mul_f32 v[46:47], v[78:79], v[46:47]
	v_pk_mul_f32 v[48:49], v[80:81], v[48:49]
	v_pk_fma_f32 v[46:47], v[94:95], v[46:47], v[110:111]
	v_pk_fma_f32 v[48:49], v[96:97], v[48:49], v[112:113]
	v_cvt_pk_bf16_f32 v46, v46, v47
	v_cvt_pk_bf16_f32 v47, v48, v49
	global_store_dwordx2 v13, v[46:47], s[44:45]
	v_pk_mul_f32 v[50:51], v[50:51], v[22:23] op_sel_hi:[1,0]
	v_pk_mul_f32 v[52:53], v[52:53], v[22:23] op_sel_hi:[1,0]
	v_pk_mul_f32 v[50:51], v[82:83], v[50:51]
	v_pk_mul_f32 v[52:53], v[84:85], v[52:53]
	v_pk_fma_f32 v[50:51], v[98:99], v[50:51], v[114:115]
	v_pk_fma_f32 v[52:53], v[100:101], v[52:53], v[116:117]
	v_cvt_pk_bf16_f32 v50, v50, v51
	v_cvt_pk_bf16_f32 v51, v52, v53
	global_store_dwordx2 v13, v[50:51], s[44:45] offset:512
	v_pk_mul_f32 v[54:55], v[54:55], v[22:23] op_sel_hi:[1,0]
	v_pk_mul_f32 v[56:57], v[56:57], v[22:23] op_sel_hi:[1,0]
	v_pk_mul_f32 v[54:55], v[86:87], v[54:55]
	v_pk_mul_f32 v[56:57], v[88:89], v[56:57]
	v_pk_fma_f32 v[54:55], v[102:103], v[54:55], v[118:119]
	v_pk_fma_f32 v[56:57], v[104:105], v[56:57], v[120:121]
	v_cvt_pk_bf16_f32 v54, v54, v55
	v_cvt_pk_bf16_f32 v55, v56, v57
	global_store_dwordx2 v13, v[54:55], s[44:45] offset:1024
	v_pk_mul_f32 v[58:59], v[58:59], v[22:23] op_sel_hi:[1,0]
	v_pk_mul_f32 v[60:61], v[60:61], v[22:23] op_sel_hi:[1,0]
	v_pk_mul_f32 v[58:59], v[90:91], v[58:59]
	v_pk_mul_f32 v[60:61], v[92:93], v[60:61]
	v_pk_fma_f32 v[58:59], v[106:107], v[58:59], v[122:123]
	v_pk_fma_f32 v[60:61], v[108:109], v[60:61], v[124:125]
	v_cvt_pk_bf16_f32 v58, v58, v59
	v_cvt_pk_bf16_f32 v59, v60, v61
	global_store_dwordx2 v13, v[58:59], s[44:45] offset:1536
	s_add_u32 s44, s44, 0x400000
	s_addc_u32 s45, s45, 0
	s_waitcnt vmcnt(8)
	v_pk_mul_f32 v[24:25], v[62:63], v[62:63]
	v_pk_mul_f32 v[26:27], v[64:65], v[64:65]
	v_pk_fma_f32 v[24:25], v[66:67], v[66:67], v[24:25]
	v_pk_fma_f32 v[26:27], v[68:69], v[68:69], v[26:27]
	v_pk_fma_f32 v[24:25], v[70:71], v[70:71], v[24:25]
	v_pk_fma_f32 v[26:27], v[72:73], v[72:73], v[26:27]
	v_pk_fma_f32 v[24:25], v[74:75], v[74:75], v[24:25]
	v_pk_fma_f32 v[26:27], v[76:77], v[76:77], v[26:27]
	v_pk_add_f32 v[24:25], v[24:25], v[26:27]
	s_nop 0
	v_add_f32_e32 v19, v24, v25
	s_nop 1
	v_add_f32_dpp v19, v19, v19 quad_perm:[1,0,3,2] row_mask:0xf bank_mask:0xf
	s_nop 1
	v_add_f32_dpp v19, v19, v19 quad_perm:[2,3,0,1] row_mask:0xf bank_mask:0xf
	s_nop 1
	v_add_f32_dpp v19, v19, v19 row_half_mirror row_mask:0xf bank_mask:0xf
	s_nop 1
	v_add_f32_dpp v19, v19, v19 row_mirror row_mask:0xf bank_mask:0xf
	ds_bpermute_b32 v20, v7, v19
	s_waitcnt lgkmcnt(0)
	v_add_f32_e32 v19, v19, v20
	ds_bpermute_b32 v20, v6, v19
	s_waitcnt lgkmcnt(0)
	v_add_f32_e32 v19, v19, v20
	v_fmamk_f32 v19, v19, 0x3a800000, v18
	v_rsq_f32_e32 v22, v19
	s_nop 0
	v_pk_mul_f32 v[62:63], v[62:63], v[22:23] op_sel_hi:[1,0]
	v_pk_mul_f32 v[64:65], v[64:65], v[22:23] op_sel_hi:[1,0]
	v_pk_mul_f32 v[62:63], v[78:79], v[62:63]
	v_pk_mul_f32 v[64:65], v[80:81], v[64:65]
	v_pk_fma_f32 v[62:63], v[94:95], v[62:63], v[110:111]
	v_pk_fma_f32 v[64:65], v[96:97], v[64:65], v[112:113]
	v_cvt_pk_bf16_f32 v62, v62, v63
	v_cvt_pk_bf16_f32 v63, v64, v65
	global_store_dwordx2 v13, v[62:63], s[44:45]
	v_pk_mul_f32 v[66:67], v[66:67], v[22:23] op_sel_hi:[1,0]
	v_pk_mul_f32 v[68:69], v[68:69], v[22:23] op_sel_hi:[1,0]
	v_pk_mul_f32 v[66:67], v[82:83], v[66:67]
	v_pk_mul_f32 v[68:69], v[84:85], v[68:69]
	v_pk_fma_f32 v[66:67], v[98:99], v[66:67], v[114:115]
	v_pk_fma_f32 v[68:69], v[100:101], v[68:69], v[116:117]
	v_cvt_pk_bf16_f32 v66, v66, v67
	v_cvt_pk_bf16_f32 v67, v68, v69
	global_store_dwordx2 v13, v[66:67], s[44:45] offset:512
	v_pk_mul_f32 v[70:71], v[70:71], v[22:23] op_sel_hi:[1,0]
	v_pk_mul_f32 v[72:73], v[72:73], v[22:23] op_sel_hi:[1,0]
	v_pk_mul_f32 v[70:71], v[86:87], v[70:71]
	v_pk_mul_f32 v[72:73], v[88:89], v[72:73]
	v_pk_fma_f32 v[70:71], v[102:103], v[70:71], v[118:119]
	v_pk_fma_f32 v[72:73], v[104:105], v[72:73], v[120:121]
	v_cvt_pk_bf16_f32 v70, v70, v71
	v_cvt_pk_bf16_f32 v71, v72, v73
	global_store_dwordx2 v13, v[70:71], s[44:45] offset:1024
	v_pk_mul_f32 v[74:75], v[74:75], v[22:23] op_sel_hi:[1,0]
	v_pk_mul_f32 v[76:77], v[76:77], v[22:23] op_sel_hi:[1,0]
	v_pk_mul_f32 v[74:75], v[90:91], v[74:75]
	v_pk_mul_f32 v[76:77], v[92:93], v[76:77]
	v_pk_fma_f32 v[74:75], v[106:107], v[74:75], v[122:123]
	v_pk_fma_f32 v[76:77], v[108:109], v[76:77], v[124:125]
	v_cvt_pk_bf16_f32 v74, v74, v75
	v_cvt_pk_bf16_f32 v75, v76, v77
	global_store_dwordx2 v13, v[74:75], s[44:45] offset:1536
	s_add_u32 s44, s44, 0x400000
	s_addc_u32 s45, s45, 0
	s_branch .LBB0_365

.LBB0_1865:
	s_cmp_lg_u32 s84, 0x100
	s_cbranch_scc1 .Lnm1_orig
	v_readlane_b32 s4, v251, 0
	v_readfirstlane_b32 s5, v135
	v_readlane_b32 s6, v249, 47
	s_lshr_b32 s5, s5, 6
	s_lshl_b32 s4, s4, 3
	s_add_i32 s4, s4, s5
	v_readlane_b32 s8, v251, 61
	v_readlane_b32 s9, v251, 62
	v_readlane_b32 s52, v250, 45
	v_readlane_b32 s53, v250, 46
	s_cmp_lg_u32 s6, 0
	s_cbranch_scc1 .Lnm1_xb
	v_readlane_b32 s8, v250, 43
	v_readlane_b32 s9, v250, 44
.Lnm1_xb:
	v_readlane_b32 s10, v251, 23
	v_readlane_b32 s11, v251, 24
	v_readlane_b32 s12, v250, 16
	v_readlane_b32 s13, v250, 17
	v_mbcnt_lo_u32_b32 v0, -1, 0
	v_mbcnt_hi_u32_b32 v0, -1, v0
	v_lshlrev_b32_e32 v12, 4, v0
	v_lshlrev_b32_e32 v13, 3, v0
	v_xor_b32_e32 v6, 32, v0
	v_lshlrev_b32_e32 v6, 2, v6
	v_xor_b32_e32 v7, 16, v0
	v_lshlrev_b32_e32 v7, 2, v7
	v_xor_b32_e32 v8, 8, v0
	v_lshlrev_b32_e32 v8, 2, v8
	v_xor_b32_e32 v9, 4, v0
	v_lshlrev_b32_e32 v9, 2, v9
	v_xor_b32_e32 v10, 2, v0
	v_lshlrev_b32_e32 v10, 2, v10
	v_xor_b32_e32 v11, 1, v0
	v_lshlrev_b32_e32 v11, 2, v11
	v_mov_b32_e32 v18, 0x358637bd
	s_lshl_b32 s14, s6, 12
	s_add_u32 s12, s12, s14
	s_addc_u32 s13, s13, 0
	s_mul_i32 s15, s6, 3
	s_mul_i32 s15, s15, 0x6000
	s_add_u32 s16, s94, 0x12d40000
	s_addc_u32 s17, s95, 0
	s_add_u32 s16, s16, s15
	s_addc_u32 s17, s17, 0
	s_lshl_b32 s14, s4, 12
	s_mov_b32 s54, s14
	s_add_u32 s18, s8, s14
	s_addc_u32 s19, s9, 0
	s_lshl_b32 s14, s4, 11
	s_add_u32 s44, s10, s14
	s_addc_u32 s45, s11, 0
	global_load_dwordx4 v[30:33], v12, s[18:19]
	global_load_dwordx4 v[34:37], v12, s[18:19] offset:1024
	global_load_dwordx4 v[38:41], v12, s[18:19] offset:2048
	global_load_dwordx4 v[42:45], v12, s[18:19] offset:3072
	s_add_u32 s18, s18, 0x800000
	s_addc_u32 s19, s19, 0
	global_load_dwordx4 v[46:49], v12, s[18:19]
	global_load_dwordx4 v[50:53], v12, s[18:19] offset:1024
	global_load_dwordx4 v[54:57], v12, s[18:19] offset:2048
	global_load_dwordx4 v[58:61], v12, s[18:19] offset:3072
	s_add_u32 s18, s18, 0x800000
	s_addc_u32 s19, s19, 0
	s_cmp_lg_u32 s6, 0
	s_cbranch_scc1 .Lnm1_x2
	s_add_u32 s18, s52, s54
	s_addc_u32 s19, s53, 0
.Lnm1_x2:
	global_load_dwordx4 v[62:65], v12, s[18:19]
	global_load_dwordx4 v[66:69], v12, s[18:19] offset:1024
	global_load_dwordx4 v[70:73], v12, s[18:19] offset:2048
	global_load_dwordx4 v[74:77], v12, s[18:19] offset:3072
	s_add_u32 s18, s18, 0x800000
	s_addc_u32 s19, s19, 0
	global_load_dwordx4 v[78:81], v12, s[12:13]
	global_load_dwordx4 v[82:85], v12, s[12:13] offset:1024
	global_load_dwordx4 v[86:89], v12, s[12:13] offset:2048
	global_load_dwordx4 v[90:93], v12, s[12:13] offset:3072
	s_add_u32 s48, s16, 0x0
	s_addc_u32 s49, s17, 0
	s_add_u32 s50, s48, 0x1000
	s_addc_u32 s51, s49, 0
	global_load_dwordx4 v[94:97], v12, s[50:51]
	global_load_dwordx4 v[98:101], v12, s[50:51] offset:1024
	global_load_dwordx4 v[102:105], v12, s[50:51] offset:2048
	global_load_dwordx4 v[106:109], v12, s[50:51] offset:3072
	global_load_dwordx4 v[110:113], v12, s[48:49]
	global_load_dwordx4 v[114:117], v12, s[48:49] offset:1024
	global_load_dwordx4 v[118:121], v12, s[48:49] offset:2048
	global_load_dwordx4 v[122:125], v12, s[48:49] offset:3072
	s_add_u32 s48, s16, 0x6000
	s_addc_u32 s49, s17, 0
	s_add_u32 s50, s48, 0x1000
	s_addc_u32 s51, s49, 0
	global_load_dwordx4 v[126:129], v12, s[50:51]
	global_load_dwordx4 v[130:133], v12, s[50:51] offset:1024
	global_load_dwordx4 v[138:141], v12, s[50:51] offset:2048
	global_load_dwordx4 v[142:145], v12, s[50:51] offset:3072
	global_load_dwordx4 v[146:149], v12, s[48:49]
	global_load_dwordx4 v[150:153], v12, s[48:49] offset:1024
	global_load_dwordx4 v[154:157], v12, s[48:49] offset:2048
	global_load_dwordx4 v[158:161], v12, s[48:49] offset:3072
	s_waitcnt vmcnt(28)
	v_pk_mul_f32 v[24:25], v[30:31], v[30:31]
	v_pk_mul_f32 v[26:27], v[32:33], v[32:33]
	v_pk_fma_f32 v[24:25], v[34:35], v[34:35], v[24:25]
	v_pk_fma_f32 v[26:27], v[36:37], v[36:37], v[26:27]
	v_pk_fma_f32 v[24:25], v[38:39], v[38:39], v[24:25]
	v_pk_fma_f32 v[26:27], v[40:41], v[40:41], v[26:27]
	v_pk_fma_f32 v[24:25], v[42:43], v[42:43], v[24:25]
	v_pk_fma_f32 v[26:27], v[44:45], v[44:45], v[26:27]
	v_pk_add_f32 v[24:25], v[24:25], v[26:27]
	s_nop 0
	v_add_f32_e32 v19, v24, v25
	s_nop 1
	v_add_f32_dpp v19, v19, v19 quad_perm:[1,0,3,2] row_mask:0xf bank_mask:0xf
	s_nop 1
	v_add_f32_dpp v19, v19, v19 quad_perm:[2,3,0,1] row_mask:0xf bank_mask:0xf
	s_nop 1
	v_add_f32_dpp v19, v19, v19 row_half_mirror row_mask:0xf bank_mask:0xf
	s_nop 1
	v_add_f32_dpp v19, v19, v19 row_mirror row_mask:0xf bank_mask:0xf
	ds_bpermute_b32 v20, v7, v19
	s_waitcnt lgkmcnt(0)
	v_add_f32_e32 v19, v19, v20
	ds_bpermute_b32 v20, v6, v19
	s_waitcnt lgkmcnt(0)
	v_add_f32_e32 v19, v19, v20
	v_fmamk_f32 v19, v19, 0x3a800000, v18
	v_rsq_f32_e32 v22, v19
	s_waitcnt vmcnt(16)
	s_waitcnt vmcnt(8)
	v_pk_add_f32 v[94:95], v[94:95], 1.0 op_sel_hi:[1,0]
	v_pk_add_f32 v[96:97], v[96:97], 1.0 op_sel_hi:[1,0]
	v_pk_add_f32 v[98:99], v[98:99], 1.0 op_sel_hi:[1,0]
	v_pk_add_f32 v[100:101], v[100:101], 1.0 op_sel_hi:[1,0]
	v_pk_add_f32 v[102:103], v[102:103], 1.0 op_sel_hi:[1,0]
	v_pk_add_f32 v[104:105], v[104:105], 1.0 op_sel_hi:[1,0]
	v_pk_add_f32 v[106:107], v[106:107], 1.0 op_sel_hi:[1,0]
	v_pk_add_f32 v[108:109], v[108:109], 1.0 op_sel_hi:[1,0]
	s_nop 0
	v_pk_mul_f32 v[30:31], v[30:31], v[22:23] op_sel_hi:[1,0]
	v_pk_mul_f32 v[32:33], v[32:33], v[22:23] op_sel_hi:[1,0]
	v_pk_mul_f32 v[30:31], v[78:79], v[30:31]
	v_pk_mul_f32 v[32:33], v[80:81], v[32:33]
	v_pk_fma_f32 v[30:31], v[94:95], v[30:31], v[110:111]
	v_pk_fma_f32 v[32:33], v[96:97], v[32:33], v[112:113]
	v_cvt_pk_bf16_f32 v30, v30, v31
	v_cvt_pk_bf16_f32 v31, v32, v33
	global_store_dwordx2 v13, v[30:31], s[44:45]
	v_pk_mul_f32 v[34:35], v[34:35], v[22:23] op_sel_hi:[1,0]
	v_pk_mul_f32 v[36:37], v[36:37], v[22:23] op_sel_hi:[1,0]
	v_pk_mul_f32 v[34:35], v[82:83], v[34:35]
	v_pk_mul_f32 v[36:37], v[84:85], v[36:37]
	v_pk_fma_f32 v[34:35], v[98:99], v[34:35], v[114:115]
	v_pk_fma_f32 v[36:37], v[100:101], v[36:37], v[116:117]
	v_cvt_pk_bf16_f32 v34, v34, v35
	v_cvt_pk_bf16_f32 v35, v36, v37
	global_store_dwordx2 v13, v[34:35], s[44:45] offset:512
	v_pk_mul_f32 v[38:39], v[38:39], v[22:23] op_sel_hi:[1,0]
	v_pk_mul_f32 v[40:41], v[40:41], v[22:23] op_sel_hi:[1,0]
	v_pk_mul_f32 v[38:39], v[86:87], v[38:39]
	v_pk_mul_f32 v[40:41], v[88:89], v[40:41]
	v_pk_fma_f32 v[38:39], v[102:103], v[38:39], v[118:119]
	v_pk_fma_f32 v[40:41], v[104:105], v[40:41], v[120:121]
	v_cvt_pk_bf16_f32 v38, v38, v39
	v_cvt_pk_bf16_f32 v39, v40, v41
	global_store_dwordx2 v13, v[38:39], s[44:45] offset:1024
	v_pk_mul_f32 v[42:43], v[42:43], v[22:23] op_sel_hi:[1,0]
	v_pk_mul_f32 v[44:45], v[44:45], v[22:23] op_sel_hi:[1,0]
	v_pk_mul_f32 v[42:43], v[90:91], v[42:43]
	v_pk_mul_f32 v[44:45], v[92:93], v[44:45]
	v_pk_fma_f32 v[42:43], v[106:107], v[42:43], v[122:123]
	v_pk_fma_f32 v[44:45], v[108:109], v[44:45], v[124:125]
	v_cvt_pk_bf16_f32 v42, v42, v43
	v_cvt_pk_bf16_f32 v43, v44, v45
	global_store_dwordx2 v13, v[42:43], s[44:45] offset:1536
	s_add_u32 s44, s44, 0x400000
	s_addc_u32 s45, s45, 0
	global_load_dwordx4 v[30:33], v12, s[18:19]
	global_load_dwordx4 v[34:37], v12, s[18:19] offset:1024
	global_load_dwordx4 v[38:41], v12, s[18:19] offset:2048
	global_load_dwordx4 v[42:45], v12, s[18:19] offset:3072
	s_add_u32 s18, s18, 0x800000
	s_addc_u32 s19, s19, 0
	s_waitcnt vmcnt(32)
	v_pk_mul_f32 v[24:25], v[46:47], v[46:47]
	v_pk_mul_f32 v[26:27], v[48:49], v[48:49]
	v_pk_fma_f32 v[24:25], v[50:51], v[50:51], v[24:25]
	v_pk_fma_f32 v[26:27], v[52:53], v[52:53], v[26:27]
	v_pk_fma_f32 v[24:25], v[54:55], v[54:55], v[24:25]
	v_pk_fma_f32 v[26:27], v[56:57], v[56:57], v[26:27]
	v_pk_fma_f32 v[24:25], v[58:59], v[58:59], v[24:25]
	v_pk_fma_f32 v[26:27], v[60:61], v[60:61], v[26:27]
	v_pk_add_f32 v[24:25], v[24:25], v[26:27]
	s_nop 0
	v_add_f32_e32 v19, v24, v25
	s_nop 1
	v_add_f32_dpp v19, v19, v19 quad_perm:[1,0,3,2] row_mask:0xf bank_mask:0xf
	s_nop 1
	v_add_f32_dpp v19, v19, v19 quad_perm:[2,3,0,1] row_mask:0xf bank_mask:0xf
	s_nop 1
	v_add_f32_dpp v19, v19, v19 row_half_mirror row_mask:0xf bank_mask:0xf
	s_nop 1
	v_add_f32_dpp v19, v19, v19 row_mirror row_mask:0xf bank_mask:0xf
	ds_bpermute_b32 v20, v7, v19
	s_waitcnt lgkmcnt(0)
	v_add_f32_e32 v19, v19, v20
	ds_bpermute_b32 v20, v6, v19
	s_waitcnt lgkmcnt(0)
	v_add_f32_e32 v19, v19, v20
	v_fmamk_f32 v19, v19, 0x3a800000, v18
	v_rsq_f32_e32 v22, v19
	s_nop 0
	v_pk_mul_f32 v[46:47], v[46:47], v[22:23] op_sel_hi:[1,0]
	v_pk_mul_f32 v[48:49], v[48:49], v[22:23] op_sel_hi:[1,0]
	v_pk_mul_f32 v[46:47], v[78:79], v[46:47]
	v_pk_mul_f32 v[48:49], v[80:81], v[48:49]
	v_pk_fma_f32 v[46:47], v[94:95], v[46:47], v[110:111]
	v_pk_fma_f32 v[48:49], v[96:97], v[48:49], v[112:113]
	v_cvt_pk_bf16_f32 v46, v46, v47
	v_cvt_pk_bf16_f32 v47, v48, v49
	global_store_dwordx2 v13, v[46:47], s[44:45]
	v_pk_mul_f32 v[50:51], v[50:51], v[22:23] op_sel_hi:[1,0]
	v_pk_mul_f32 v[52:53], v[52:53], v[22:23] op_sel_hi:[1,0]
	v_pk_mul_f32 v[50:51], v[82:83], v[50:51]
	v_pk_mul_f32 v[52:53], v[84:85], v[52:53]
	v_pk_fma_f32 v[50:51], v[98:99], v[50:51], v[114:115]
	v_pk_fma_f32 v[52:53], v[100:101], v[52:53], v[116:117]
	v_cvt_pk_bf16_f32 v50, v50, v51
	v_cvt_pk_bf16_f32 v51, v52, v53
	global_store_dwordx2 v13, v[50:51], s[44:45] offset:512
	v_pk_mul_f32 v[54:55], v[54:55], v[22:23] op_sel_hi:[1,0]
	v_pk_mul_f32 v[56:57], v[56:57], v[22:23] op_sel_hi:[1,0]
	v_pk_mul_f32 v[54:55], v[86:87], v[54:55]
	v_pk_mul_f32 v[56:57], v[88:89], v[56:57]
	v_pk_fma_f32 v[54:55], v[102:103], v[54:55], v[118:119]
	v_pk_fma_f32 v[56:57], v[104:105], v[56:57], v[120:121]
	v_cvt_pk_bf16_f32 v54, v54, v55
	v_cvt_pk_bf16_f32 v55, v56, v57
	global_store_dwordx2 v13, v[54:55], s[44:45] offset:1024
	v_pk_mul_f32 v[58:59], v[58:59], v[22:23] op_sel_hi:[1,0]
	v_pk_mul_f32 v[60:61], v[60:61], v[22:23] op_sel_hi:[1,0]
	v_pk_mul_f32 v[58:59], v[90:91], v[58:59]
	v_pk_mul_f32 v[60:61], v[92:93], v[60:61]
	v_pk_fma_f32 v[58:59], v[106:107], v[58:59], v[122:123]
	v_pk_fma_f32 v[60:61], v[108:109], v[60:61], v[124:125]
	v_cvt_pk_bf16_f32 v58, v58, v59
	v_cvt_pk_bf16_f32 v59, v60, v61
	global_store_dwordx2 v13, v[58:59], s[44:45] offset:1536
	s_add_u32 s44, s44, 0x400000
	s_addc_u32 s45, s45, 0
	global_load_dwordx4 v[46:49], v12, s[18:19]
	global_load_dwordx4 v[50:53], v12, s[18:19] offset:1024
	global_load_dwordx4 v[54:57], v12, s[18:19] offset:2048
	global_load_dwordx4 v[58:61], v12, s[18:19] offset:3072
	s_add_u32 s18, s18, 0x800000
	s_addc_u32 s19, s19, 0
	s_add_u32 s48, s16, 0xc000
	s_addc_u32 s49, s17, 0
	s_add_u32 s50, s48, 0x1000
	s_addc_u32 s51, s49, 0
	global_load_dwordx4 v[94:97], v12, s[50:51]
	global_load_dwordx4 v[98:101], v12, s[50:51] offset:1024
	global_load_dwordx4 v[102:105], v12, s[50:51] offset:2048
	global_load_dwordx4 v[106:109], v12, s[50:51] offset:3072
	global_load_dwordx4 v[110:113], v12, s[48:49]
	global_load_dwordx4 v[114:117], v12, s[48:49] offset:1024
	global_load_dwordx4 v[118:121], v12, s[48:49] offset:2048
	global_load_dwordx4 v[122:125], v12, s[48:49] offset:3072
	s_waitcnt vmcnt(44)
	v_pk_mul_f32 v[24:25], v[62:63], v[62:63]
	v_pk_mul_f32 v[26:27], v[64:65], v[64:65]
	v_pk_fma_f32 v[24:25], v[66:67], v[66:67], v[24:25]
	v_pk_fma_f32 v[26:27], v[68:69], v[68:69], v[26:27]
	v_pk_fma_f32 v[24:25], v[70:71], v[70:71], v[24:25]
	v_pk_fma_f32 v[26:27], v[72:73], v[72:73], v[26:27]
	v_pk_fma_f32 v[24:25], v[74:75], v[74:75], v[24:25]
	v_pk_fma_f32 v[26:27], v[76:77], v[76:77], v[26:27]
	v_pk_add_f32 v[24:25], v[24:25], v[26:27]
	s_nop 0
	v_add_f32_e32 v19, v24, v25
	s_nop 1
	v_add_f32_dpp v19, v19, v19 quad_perm:[1,0,3,2] row_mask:0xf bank_mask:0xf
	s_nop 1
	v_add_f32_dpp v19, v19, v19 quad_perm:[2,3,0,1] row_mask:0xf bank_mask:0xf
	s_nop 1
	v_add_f32_dpp v19, v19, v19 row_half_mirror row_mask:0xf bank_mask:0xf
	s_nop 1
	v_add_f32_dpp v19, v19, v19 row_mirror row_mask:0xf bank_mask:0xf
	ds_bpermute_b32 v20, v7, v19
	s_waitcnt lgkmcnt(0)
	v_add_f32_e32 v19, v19, v20
	ds_bpermute_b32 v20, v6, v19
	s_waitcnt lgkmcnt(0)
	v_add_f32_e32 v19, v19, v20
	v_fmamk_f32 v19, v19, 0x3a800000, v18
	v_rsq_f32_e32 v22, v19
	s_waitcnt vmcnt(24)
	v_pk_add_f32 v[126:127], v[126:127], 1.0 op_sel_hi:[1,0]
	v_pk_add_f32 v[128:129], v[128:129], 1.0 op_sel_hi:[1,0]
	v_pk_add_f32 v[130:131], v[130:131], 1.0 op_sel_hi:[1,0]
	v_pk_add_f32 v[132:133], v[132:133], 1.0 op_sel_hi:[1,0]
	v_pk_add_f32 v[138:139], v[138:139], 1.0 op_sel_hi:[1,0]
	v_pk_add_f32 v[140:141], v[140:141], 1.0 op_sel_hi:[1,0]
	v_pk_add_f32 v[142:143], v[142:143], 1.0 op_sel_hi:[1,0]
	v_pk_add_f32 v[144:145], v[144:145], 1.0 op_sel_hi:[1,0]
	s_nop 0
	v_pk_mul_f32 v[62:63], v[62:63], v[22:23] op_sel_hi:[1,0]
	v_pk_mul_f32 v[64:65], v[64:65], v[22:23] op_sel_hi:[1,0]
	v_pk_mul_f32 v[62:63], v[78:79], v[62:63]
	v_pk_mul_f32 v[64:65], v[80:81], v[64:65]
	v_pk_fma_f32 v[62:63], v[126:127], v[62:63], v[146:147]
	v_pk_fma_f32 v[64:65], v[128:129], v[64:65], v[148:149]
	v_cvt_pk_bf16_f32 v62, v62, v63
	v_cvt_pk_bf16_f32 v63, v64, v65
	global_store_dwordx2 v13, v[62:63], s[44:45]
	v_pk_mul_f32 v[66:67], v[66:67], v[22:23] op_sel_hi:[1,0]
	v_pk_mul_f32 v[68:69], v[68:69], v[22:23] op_sel_hi:[1,0]
	v_pk_mul_f32 v[66:67], v[82:83], v[66:67]
	v_pk_mul_f32 v[68:69], v[84:85], v[68:69]
	v_pk_fma_f32 v[66:67], v[130:131], v[66:67], v[150:151]
	v_pk_fma_f32 v[68:69], v[132:133], v[68:69], v[152:153]
	v_cvt_pk_bf16_f32 v66, v66, v67
	v_cvt_pk_bf16_f32 v67, v68, v69
	global_store_dwordx2 v13, v[66:67], s[44:45] offset:512
	v_pk_mul_f32 v[70:71], v[70:71], v[22:23] op_sel_hi:[1,0]
	v_pk_mul_f32 v[72:73], v[72:73], v[22:23] op_sel_hi:[1,0]
	v_pk_mul_f32 v[70:71], v[86:87], v[70:71]
	v_pk_mul_f32 v[72:73], v[88:89], v[72:73]
	v_pk_fma_f32 v[70:71], v[138:139], v[70:71], v[154:155]
	v_pk_fma_f32 v[72:73], v[140:141], v[72:73], v[156:157]
	v_cvt_pk_bf16_f32 v70, v70, v71
	v_cvt_pk_bf16_f32 v71, v72, v73
	global_store_dwordx2 v13, v[70:71], s[44:45] offset:1024
	v_pk_mul_f32 v[74:75], v[74:75], v[22:23] op_sel_hi:[1,0]
	v_pk_mul_f32 v[76:77], v[76:77], v[22:23] op_sel_hi:[1,0]
	v_pk_mul_f32 v[74:75], v[90:91], v[74:75]
	v_pk_mul_f32 v[76:77], v[92:93], v[76:77]
	v_pk_fma_f32 v[74:75], v[142:143], v[74:75], v[158:159]
	v_pk_fma_f32 v[76:77], v[144:145], v[76:77], v[160:161]
	v_cvt_pk_bf16_f32 v74, v74, v75
	v_cvt_pk_bf16_f32 v75, v76, v77
	global_store_dwordx2 v13, v[74:75], s[44:45] offset:1536
	s_add_u32 s44, s44, 0x400000
	s_addc_u32 s45, s45, 0
	global_load_dwordx4 v[62:65], v12, s[18:19]
	global_load_dwordx4 v[66:69], v12, s[18:19] offset:1024
	global_load_dwordx4 v[70:73], v12, s[18:19] offset:2048
	global_load_dwordx4 v[74:77], v12, s[18:19] offset:3072
	s_add_u32 s18, s18, 0x800000
	s_addc_u32 s19, s19, 0
	s_waitcnt vmcnt(24)
	v_pk_mul_f32 v[24:25], v[30:31], v[30:31]
	v_pk_mul_f32 v[26:27], v[32:33], v[32:33]
	v_pk_fma_f32 v[24:25], v[34:35], v[34:35], v[24:25]
	v_pk_fma_f32 v[26:27], v[36:37], v[36:37], v[26:27]
	v_pk_fma_f32 v[24:25], v[38:39], v[38:39], v[24:25]
	v_pk_fma_f32 v[26:27], v[40:41], v[40:41], v[26:27]
	v_pk_fma_f32 v[24:25], v[42:43], v[42:43], v[24:25]
	v_pk_fma_f32 v[26:27], v[44:45], v[44:45], v[26:27]
	v_pk_add_f32 v[24:25], v[24:25], v[26:27]
	s_nop 0
	v_add_f32_e32 v19, v24, v25
	s_nop 1
	v_add_f32_dpp v19, v19, v19 quad_perm:[1,0,3,2] row_mask:0xf bank_mask:0xf
	s_nop 1
	v_add_f32_dpp v19, v19, v19 quad_perm:[2,3,0,1] row_mask:0xf bank_mask:0xf
	s_nop 1
	v_add_f32_dpp v19, v19, v19 row_half_mirror row_mask:0xf bank_mask:0xf
	s_nop 1
	v_add_f32_dpp v19, v19, v19 row_mirror row_mask:0xf bank_mask:0xf
	ds_bpermute_b32 v20, v7, v19
	s_waitcnt lgkmcnt(0)
	v_add_f32_e32 v19, v19, v20
	ds_bpermute_b32 v20, v6, v19
	s_waitcnt lgkmcnt(0)
	v_add_f32_e32 v19, v19, v20
	v_fmamk_f32 v19, v19, 0x3a800000, v18
	v_rsq_f32_e32 v22, v19
	s_nop 0
	v_pk_mul_f32 v[30:31], v[30:31], v[22:23] op_sel_hi:[1,0]
	v_pk_mul_f32 v[32:33], v[32:33], v[22:23] op_sel_hi:[1,0]
	v_pk_mul_f32 v[30:31], v[78:79], v[30:31]
	v_pk_mul_f32 v[32:33], v[80:81], v[32:33]
	v_pk_fma_f32 v[30:31], v[126:127], v[30:31], v[146:147]
	v_pk_fma_f32 v[32:33], v[128:129], v[32:33], v[148:149]
	v_cvt_pk_bf16_f32 v30, v30, v31
	v_cvt_pk_bf16_f32 v31, v32, v33
	global_store_dwordx2 v13, v[30:31], s[44:45]
	v_pk_mul_f32 v[34:35], v[34:35], v[22:23] op_sel_hi:[1,0]
	v_pk_mul_f32 v[36:37], v[36:37], v[22:23] op_sel_hi:[1,0]
	v_pk_mul_f32 v[34:35], v[82:83], v[34:35]
	v_pk_mul_f32 v[36:37], v[84:85], v[36:37]
	v_pk_fma_f32 v[34:35], v[130:131], v[34:35], v[150:151]
	v_pk_fma_f32 v[36:37], v[132:133], v[36:37], v[152:153]
	v_cvt_pk_bf16_f32 v34, v34, v35
	v_cvt_pk_bf16_f32 v35, v36, v37
	global_store_dwordx2 v13, v[34:35], s[44:45] offset:512
	v_pk_mul_f32 v[38:39], v[38:39], v[22:23] op_sel_hi:[1,0]
	v_pk_mul_f32 v[40:41], v[40:41], v[22:23] op_sel_hi:[1,0]
	v_pk_mul_f32 v[38:39], v[86:87], v[38:39]
	v_pk_mul_f32 v[40:41], v[88:89], v[40:41]
	v_pk_fma_f32 v[38:39], v[138:139], v[38:39], v[154:155]
	v_pk_fma_f32 v[40:41], v[140:141], v[40:41], v[156:157]
	v_cvt_pk_bf16_f32 v38, v38, v39
	v_cvt_pk_bf16_f32 v39, v40, v41
	global_store_dwordx2 v13, v[38:39], s[44:45] offset:1024
	v_pk_mul_f32 v[42:43], v[42:43], v[22:23] op_sel_hi:[1,0]
	v_pk_mul_f32 v[44:45], v[44:45], v[22:23] op_sel_hi:[1,0]
	v_pk_mul_f32 v[42:43], v[90:91], v[42:43]
	v_pk_mul_f32 v[44:45], v[92:93], v[44:45]
	v_pk_fma_f32 v[42:43], v[142:143], v[42:43], v[158:159]
	v_pk_fma_f32 v[44:45], v[144:145], v[44:45], v[160:161]
	v_cvt_pk_bf16_f32 v42, v42, v43
	v_cvt_pk_bf16_f32 v43, v44, v45
	global_store_dwordx2 v13, v[42:43], s[44:45] offset:1536
	s_add_u32 s44, s44, 0x400000
	s_addc_u32 s45, s45, 0
	s_waitcnt vmcnt(20)
	v_pk_mul_f32 v[24:25], v[46:47], v[46:47]
	v_pk_mul_f32 v[26:27], v[48:49], v[48:49]
	v_pk_fma_f32 v[24:25], v[50:51], v[50:51], v[24:25]
	v_pk_fma_f32 v[26:27], v[52:53], v[52:53], v[26:27]
	v_pk_fma_f32 v[24:25], v[54:55], v[54:55], v[24:25]
	v_pk_fma_f32 v[26:27], v[56:57], v[56:57], v[26:27]
	v_pk_fma_f32 v[24:25], v[58:59], v[58:59], v[24:25]
	v_pk_fma_f32 v[26:27], v[60:61], v[60:61], v[26:27]
	v_pk_add_f32 v[24:25], v[24:25], v[26:27]
	s_nop 0
	v_add_f32_e32 v19, v24, v25
	s_nop 1
	v_add_f32_dpp v19, v19, v19 quad_perm:[1,0,3,2] row_mask:0xf bank_mask:0xf
	s_nop 1
	v_add_f32_dpp v19, v19, v19 quad_perm:[2,3,0,1] row_mask:0xf bank_mask:0xf
	s_nop 1
	v_add_f32_dpp v19, v19, v19 row_half_mirror row_mask:0xf bank_mask:0xf
	s_nop 1
	v_add_f32_dpp v19, v19, v19 row_mirror row_mask:0xf bank_mask:0xf
	ds_bpermute_b32 v20, v7, v19
	s_waitcnt lgkmcnt(0)
	v_add_f32_e32 v19, v19, v20
	ds_bpermute_b32 v20, v6, v19
	s_waitcnt lgkmcnt(0)
	v_add_f32_e32 v19, v19, v20
	v_fmamk_f32 v19, v19, 0x3a800000, v18
	v_rsq_f32_e32 v22, v19
	s_waitcnt vmcnt(12)
	v_pk_add_f32 v[94:95], v[94:95], 1.0 op_sel_hi:[1,0]
	v_pk_add_f32 v[96:97], v[96:97], 1.0 op_sel_hi:[1,0]
	v_pk_add_f32 v[98:99], v[98:99], 1.0 op_sel_hi:[1,0]
	v_pk_add_f32 v[100:101], v[100:101], 1.0 op_sel_hi:[1,0]
	v_pk_add_f32 v[102:103], v[102:103], 1.0 op_sel_hi:[1,0]
	v_pk_add_f32 v[104:105], v[104:105], 1.0 op_sel_hi:[1,0]
	v_pk_add_f32 v[106:107], v[106:107], 1.0 op_sel_hi:[1,0]
	v_pk_add_f32 v[108:109], v[108:109], 1.0 op_sel_hi:[1,0]
	s_nop 0
	v_pk_mul_f32 v[46:47], v[46:47], v[22:23] op_sel_hi:[1,0]
	v_pk_mul_f32 v[48:49], v[48:49], v[22:23] op_sel_hi:[1,0]
	v_pk_mul_f32 v[46:47], v[78:79], v[46:47]
	v_pk_mul_f32 v[48:49], v[80:81], v[48:49]
	v_pk_fma_f32 v[46:47], v[94:95], v[46:47], v[110:111]
	v_pk_fma_f32 v[48:49], v[96:97], v[48:49], v[112:113]
	v_cvt_pk_bf16_f32 v46, v46, v47
	v_cvt_pk_bf16_f32 v47, v48, v49
	global_store_dwordx2 v13, v[46:47], s[44:45]
	v_pk_mul_f32 v[50:51], v[50:51], v[22:23] op_sel_hi:[1,0]
	v_pk_mul_f32 v[52:53], v[52:53], v[22:23] op_sel_hi:[1,0]
	v_pk_mul_f32 v[50:51], v[82:83], v[50:51]
	v_pk_mul_f32 v[52:53], v[84:85], v[52:53]
	v_pk_fma_f32 v[50:51], v[98:99], v[50:51], v[114:115]
	v_pk_fma_f32 v[52:53], v[100:101], v[52:53], v[116:117]
	v_cvt_pk_bf16_f32 v50, v50, v51
	v_cvt_pk_bf16_f32 v51, v52, v53
	global_store_dwordx2 v13, v[50:51], s[44:45] offset:512
	v_pk_mul_f32 v[54:55], v[54:55], v[22:23] op_sel_hi:[1,0]
	v_pk_mul_f32 v[56:57], v[56:57], v[22:23] op_sel_hi:[1,0]
	v_pk_mul_f32 v[54:55], v[86:87], v[54:55]
	v_pk_mul_f32 v[56:57], v[88:89], v[56:57]
	v_pk_fma_f32 v[54:55], v[102:103], v[54:55], v[118:119]
	v_pk_fma_f32 v[56:57], v[104:105], v[56:57], v[120:121]
	v_cvt_pk_bf16_f32 v54, v54, v55
	v_cvt_pk_bf16_f32 v55, v56, v57
	global_store_dwordx2 v13, v[54:55], s[44:45] offset:1024
	v_pk_mul_f32 v[58:59], v[58:59], v[22:23] op_sel_hi:[1,0]
	v_pk_mul_f32 v[60:61], v[60:61], v[22:23] op_sel_hi:[1,0]
	v_pk_mul_f32 v[58:59], v[90:91], v[58:59]
	v_pk_mul_f32 v[60:61], v[92:93], v[60:61]
	v_pk_fma_f32 v[58:59], v[106:107], v[58:59], v[122:123]
	v_pk_fma_f32 v[60:61], v[108:109], v[60:61], v[124:125]
	v_cvt_pk_bf16_f32 v58, v58, v59
	v_cvt_pk_bf16_f32 v59, v60, v61
	global_store_dwordx2 v13, v[58:59], s[44:45] offset:1536
	s_add_u32 s44, s44, 0x400000
	s_addc_u32 s45, s45, 0
	s_waitcnt vmcnt(8)
	v_pk_mul_f32 v[24:25], v[62:63], v[62:63]
	v_pk_mul_f32 v[26:27], v[64:65], v[64:65]
	v_pk_fma_f32 v[24:25], v[66:67], v[66:67], v[24:25]
	v_pk_fma_f32 v[26:27], v[68:69], v[68:69], v[26:27]
	v_pk_fma_f32 v[24:25], v[70:71], v[70:71], v[24:25]
	v_pk_fma_f32 v[26:27], v[72:73], v[72:73], v[26:27]
	v_pk_fma_f32 v[24:25], v[74:75], v[74:75], v[24:25]
	v_pk_fma_f32 v[26:27], v[76:77], v[76:77], v[26:27]
	v_pk_add_f32 v[24:25], v[24:25], v[26:27]
	s_nop 0
	v_add_f32_e32 v19, v24, v25
	s_nop 1
	v_add_f32_dpp v19, v19, v19 quad_perm:[1,0,3,2] row_mask:0xf bank_mask:0xf
	s_nop 1
	v_add_f32_dpp v19, v19, v19 quad_perm:[2,3,0,1] row_mask:0xf bank_mask:0xf
	s_nop 1
	v_add_f32_dpp v19, v19, v19 row_half_mirror row_mask:0xf bank_mask:0xf
	s_nop 1
	v_add_f32_dpp v19, v19, v19 row_mirror row_mask:0xf bank_mask:0xf
	ds_bpermute_b32 v20, v7, v19
	s_waitcnt lgkmcnt(0)
	v_add_f32_e32 v19, v19, v20
	ds_bpermute_b32 v20, v6, v19
	s_waitcnt lgkmcnt(0)
	v_add_f32_e32 v19, v19, v20
	v_fmamk_f32 v19, v19, 0x3a800000, v18
	v_rsq_f32_e32 v22, v19
	s_nop 0
	v_pk_mul_f32 v[62:63], v[62:63], v[22:23] op_sel_hi:[1,0]
	v_pk_mul_f32 v[64:65], v[64:65], v[22:23] op_sel_hi:[1,0]
	v_pk_mul_f32 v[62:63], v[78:79], v[62:63]
	v_pk_mul_f32 v[64:65], v[80:81], v[64:65]
	v_pk_fma_f32 v[62:63], v[94:95], v[62:63], v[110:111]
	v_pk_fma_f32 v[64:65], v[96:97], v[64:65], v[112:113]
	v_cvt_pk_bf16_f32 v62, v62, v63
	v_cvt_pk_bf16_f32 v63, v64, v65
	global_store_dwordx2 v13, v[62:63], s[44:45]
	v_pk_mul_f32 v[66:67], v[66:67], v[22:23] op_sel_hi:[1,0]
	v_pk_mul_f32 v[68:69], v[68:69], v[22:23] op_sel_hi:[1,0]
	v_pk_mul_f32 v[66:67], v[82:83], v[66:67]
	v_pk_mul_f32 v[68:69], v[84:85], v[68:69]
	v_pk_fma_f32 v[66:67], v[98:99], v[66:67], v[114:115]
	v_pk_fma_f32 v[68:69], v[100:101], v[68:69], v[116:117]
	v_cvt_pk_bf16_f32 v66, v66, v67
	v_cvt_pk_bf16_f32 v67, v68, v69
	global_store_dwordx2 v13, v[66:67], s[44:45] offset:512
	v_pk_mul_f32 v[70:71], v[70:71], v[22:23] op_sel_hi:[1,0]
	v_pk_mul_f32 v[72:73], v[72:73], v[22:23] op_sel_hi:[1,0]
	v_pk_mul_f32 v[70:71], v[86:87], v[70:71]
	v_pk_mul_f32 v[72:73], v[88:89], v[72:73]
	v_pk_fma_f32 v[70:71], v[102:103], v[70:71], v[118:119]
	v_pk_fma_f32 v[72:73], v[104:105], v[72:73], v[120:121]
	v_cvt_pk_bf16_f32 v70, v70, v71
	v_cvt_pk_bf16_f32 v71, v72, v73
	global_store_dwordx2 v13, v[70:71], s[44:45] offset:1024
	v_pk_mul_f32 v[74:75], v[74:75], v[22:23] op_sel_hi:[1,0]
	v_pk_mul_f32 v[76:77], v[76:77], v[22:23] op_sel_hi:[1,0]
	v_pk_mul_f32 v[74:75], v[90:91], v[74:75]
	v_pk_mul_f32 v[76:77], v[92:93], v[76:77]
	v_pk_fma_f32 v[74:75], v[106:107], v[74:75], v[122:123]
	v_pk_fma_f32 v[76:77], v[108:109], v[76:77], v[124:125]
	v_cvt_pk_bf16_f32 v74, v74, v75
	v_cvt_pk_bf16_f32 v75, v76, v77
	global_store_dwordx2 v13, v[74:75], s[44:45] offset:1536
	s_add_u32 s44, s44, 0x400000
	s_addc_u32 s45, s45, 0
	v_readlane_b32 s4, v250, 43
	v_readlane_b32 s5, v250, 44
	s_branch .LBB0_1873
